# SwiGLU epilogue v2 (next-unit row-sum prefetch, 27 instr per 4 outputs) + FoX loop accumulators kept in place (no per-tile copies) + vectorised selection
# speedup vs baseline: 1.0244x; 1.0083x over previous
; template <int MODE>
; DI void bias_init(f32x16& s0, f32x16& s1, const TP& tp, float fbm, int hi) {
; #pragma unroll
;     for (int r = 0; r < 16; ++r) {
;         const int kvc = 16 * (r >> 3) + (r & 7);
;         if (MODE == 0) { s0[r] = __builtin_fmaf(-L2E, tp.cs[kvc + 8 * hi], fbm); s1[r] = __builtin_fmaf(-L2E, tp.cs[kvc + 32 + 8 * hi], fbm); }
;         else { s0[r] = __builtin_fmaf(tp.sl, (float)kvc, fbm); s1[r] = __builtin_fmaf(tp.sl, (float)(kvc + 32), fbm); }
;     }
; }
; DI float max3_asm(float a, float b, float c) { float r; asm("v_max3_f32 %0, %1, %2, %3" : "=v"(r) : "v"(a), "v"(b), "v"(c)); return r; }
; template <bool MASK>
; DI float mask_rowmax(f32x16& s0, f32x16& s1, const TP& tp) {
;     if (MASK) {
; #pragma unroll
;         for (int r = 0; r < 16; ++r) {
;             const int kvc = 16 * (r >> 3) + (r & 7);
;             const bool v0 = tp.sel && (kvc <= tp.lim) && (kvc > tp.lim2), v1 = tp.sel && (kvc + 32 <= tp.lim) && (kvc + 32 > tp.lim2);
;             s0[r] = v0 ? s0[r] : -1e30f; s1[r] = v1 ? s1[r] : -1e30f;
;         }
;     }
;     const float seed = __builtin_fminf(s0[15], s1[15]);
;     float ma = seed, mb = seed;
; #pragma unroll
;     for (int r = 0; r < 16; r += 2) { ma = max3_asm(ma, s0[r], s1[r]); mb = max3_asm(mb, s0[r + 1], s1[r + 1]); }
;     const float mx = fmaxf(ma, mb);
;     return fmaxf(mx, __shfl_xor(mx, 32));
; }
; template <int MODE, bool MASK, bool WITH_O>
; DI void attn_tile_t(lptr Kt, lptr Vt, const bf16x8 (&qf)[4], f32x16& o0, f32x16& o1, RowState& rs, const TP& tp, int lane) {
;     const int hi = lane >> 5;
;     f32x16 s0, s1;
;     bias_init<MODE>(s0, s1, tp, tp.fb - rs.mref, hi);
;     qk_acc(Kt, qf, s0, s1, lane);
;     const float mx = mask_rowmax<MASK>(s0, s1, tp);
;     const bool was = rs.seen; rs.seen = was || (mx > -1e29f);
;     const bool trig = (mx > 8.f) || (!was && mx > -1e29f && mx < -8.f);
;     if (__builtin_expect(__any(trig), 0)) {
.LBB0_493:
	s_lshl_b32 s2, s55, 8
	s_add_i32 s26, s2, 0
	s_mul_i32 s2, s55, 0x2300
	s_add_i32 s56, s26, s2
	s_mov_b64 s[2:3], -1
	s_cmp_le_i32 s31, s42
	v_sub_f32_e32 v156, v157, v160
	v_add3_u32 v161, s56, v131, v133
	v_lshl_add_u32 v162, v126, 2, s26
	s_cbranch_scc0 .LBB0_498
	ds_read_b128 v[34:37], v162 offset:36992
	ds_read_b128 v[38:41], v162 offset:36864
	ds_read_b128 v[42:45], v162 offset:36880
	ds_read_b128 v[46:49], v162 offset:37008
	ds_read_b128 v[50:53], v162 offset:36928
	ds_read_b128 v[54:57], v162 offset:37056
	ds_read_b128 v[58:61], v162 offset:36944
	ds_read_b128 v[62:65], v162 offset:37072
	s_waitcnt lgkmcnt(5)
	v_pk_fma_f32 v[88:89], v[44:45], s[80:81], v[156:157] op_sel_hi:[1,0,0]
	s_waitcnt lgkmcnt(3)
	v_pk_fma_f32 v[92:93], v[52:53], s[80:81], v[156:157] op_sel_hi:[1,0,0]
	v_pk_fma_f32 v[84:85], v[40:41], s[80:81], v[156:157] op_sel_hi:[1,0,0]
	s_waitcnt lgkmcnt(1)
	v_pk_fma_f32 v[96:97], v[60:61], s[80:81], v[156:157] op_sel_hi:[1,0,0]
	v_pk_fma_f32 v[94:95], v[58:59], s[80:81], v[156:157] op_sel_hi:[1,0,0]
	v_pk_fma_f32 v[90:91], v[50:51], s[80:81], v[156:157] op_sel_hi:[1,0,0]
	v_pk_fma_f32 v[86:87], v[42:43], s[80:81], v[156:157] op_sel_hi:[1,0,0]
	v_pk_fma_f32 v[82:83], v[38:39], s[80:81], v[156:157] op_sel_hi:[1,0,0]
	s_waitcnt lgkmcnt(0)
	v_pk_fma_f32 v[80:81], v[64:65], s[80:81], v[156:157] op_sel_hi:[1,0,0]
	v_pk_fma_f32 v[76:77], v[56:57], s[80:81], v[156:157] op_sel_hi:[1,0,0]
	v_pk_fma_f32 v[72:73], v[48:49], s[80:81], v[156:157] op_sel_hi:[1,0,0]
	v_pk_fma_f32 v[68:69], v[36:37], s[80:81], v[156:157] op_sel_hi:[1,0,0]
	v_pk_fma_f32 v[78:79], v[62:63], s[80:81], v[156:157] op_sel_hi:[1,0,0]
	v_pk_fma_f32 v[74:75], v[54:55], s[80:81], v[156:157] op_sel_hi:[1,0,0]
	v_pk_fma_f32 v[70:71], v[46:47], s[80:81], v[156:157] op_sel_hi:[1,0,0]
	v_pk_fma_f32 v[66:67], v[34:35], s[80:81], v[156:157] op_sel_hi:[1,0,0]
	ds_read_b128 v[34:37], v161 offset:4608
	ds_read_b128 v[38:41], v161
	ds_read_b128 v[42:45], v161 offset:32
	ds_read_b128 v[46:49], v161 offset:4640
	ds_read_b128 v[50:53], v161 offset:64
	ds_read_b128 v[54:57], v161 offset:4672
	ds_read_b128 v[58:61], v161 offset:96
	ds_read_b128 v[62:65], v161 offset:4704
	s_setprio 1
	s_waitcnt lgkmcnt(6)
	v_mfma_f32_32x32x16_bf16 v[82:97], v[38:41], v[98:101], v[82:97]
	v_mfma_f32_32x32x16_bf16 v[66:81], v[34:37], v[98:101], v[66:81]
	s_waitcnt lgkmcnt(5)
	v_mfma_f32_32x32x16_bf16 v[82:97], v[42:45], v[102:105], v[82:97]
	s_waitcnt lgkmcnt(4)
	v_mfma_f32_32x32x16_bf16 v[66:81], v[46:49], v[102:105], v[66:81]
	s_waitcnt lgkmcnt(3)
	v_mfma_f32_32x32x16_bf16 v[82:97], v[50:53], v[106:109], v[82:97]
	s_waitcnt lgkmcnt(2)
	v_mfma_f32_32x32x16_bf16 v[66:81], v[54:57], v[106:109], v[66:81]
	s_waitcnt lgkmcnt(1)
	v_mfma_f32_32x32x16_bf16 v[82:97], v[58:61], v[110:113], v[82:97]
	s_waitcnt lgkmcnt(0)
	v_mfma_f32_32x32x16_bf16 v[66:81], v[62:65], v[110:113], v[66:81]
	s_setprio 0
	s_nop 10
	v_max_f32_e32 v34, v81, v81
	v_max_f32_e32 v35, v97, v97
	v_min_f32_e32 v34, v35, v34
	v_max3_f32 v35, v34, v82, v66
	v_max3_f32 v34, v34, v83, v67
	v_and_b32_e32 v36, 64, v209
	v_max3_f32 v35, v35, v84, v68
	v_max3_f32 v34, v34, v85, v69
	v_add_u32_e32 v36, 64, v36
	v_max3_f32 v35, v35, v86, v70
	v_max3_f32 v34, v34, v87, v71
	s_mov_b32 s2, 0xefa18f08
	v_max3_f32 v35, v35, v88, v72
	v_max3_f32 v34, v34, v89, v73
	s_mov_b64 s[28:29], -1
	v_max3_f32 v35, v35, v90, v74
	v_max3_f32 v34, v34, v91, v75
	s_nop 0
	v_max3_f32 v35, v35, v92, v76
	v_max3_f32 v34, v34, v93, v77
	s_nop 0
	v_max3_f32 v35, v35, v94, v78
	v_max3_f32 v34, v34, v95, v79
	s_nop 0
	v_max3_f32 v35, v35, v96, v80
	v_max3_f32 v34, v34, v97, v81
	s_nop 0
	v_max_f32_e32 v34, v34, v34
	v_max_f32_e32 v35, v35, v35
	v_max_f32_e32 v34, v35, v34
	v_xor_b32_e32 v35, 32, v209
	v_cmp_lt_i32_e32 vcc, v35, v36
	s_nop 1
	v_cndmask_b32_e32 v35, v209, v35, vcc
	v_lshlrev_b32_e32 v35, 2, v35
	ds_bpermute_b32 v35, v35, v34
	s_waitcnt lgkmcnt(0)
	v_max_f32_e32 v35, v35, v35
	v_max_f32_e32 v165, v34, v35
	v_cmp_lt_f32_e64 s[26:27], s2, v165
	s_mov_b32 s2, 0x41000000
	v_cmp_nlt_f32_e32 vcc, s2, v165
	s_and_saveexec_b64 s[2:3], vcc
	s_mov_b32 s28, 0xc1000000
	v_cmp_gt_f32_e32 vcc, s28, v165
	s_xor_b64 s[28:29], s[22:23], -1
	s_and_b64 s[28:29], vcc, s[28:29]
	s_and_b64 s[28:29], s[26:27], s[28:29]
	s_orn2_b64 s[28:29], s[28:29], exec
	s_or_b64 exec, exec, s[2:3]
	v_cndmask_b32_e64 v34, 0, 1, s[28:29]
	v_cmp_ne_u32_e32 vcc, 0, v34
	v_mov_b32_e32 v163, v160
	v_mov_b32_e32 v164, v159
	s_cbranch_vccnz .LBB0_514
; template <int MODE, bool MASK, bool WITH_O>
; DI void attn_tile_t(lptr Kt, lptr Vt, const bf16x8 (&qf)[4], f32x16& o0, f32x16& o1, RowState& rs, const TP& tp, int lane) {
;     ...
;     } else {
;         const int i = lane & 31;
;         lptr vp = Vt + i * KPB + hi * 16;
;         float sum = 0.f;
;     ...
;         PV_STEP(s0, 0, 0) PV_STEP(s0, 8, 32) PV_STEP(s1, 0, 64) PV_STEP(s1, 8, 96)
;     ...
;         rs.l += sum;
.LBB0_497:
	v_exp_f32_e32 v82, v82
	v_exp_f32_e32 v83, v83
	v_add3_u32 v165, s56, v135, v141
	v_exp_f32_e32 v84, v84
	ds_read_b128 v[166:169], v165 offset:18432
	ds_read_b128 v[216:219], v165 offset:23040
	v_exp_f32_e32 v85, v85
	v_exp_f32_e32 v86, v86
	v_exp_f32_e32 v87, v87
	v_exp_f32_e32 v88, v88
	v_exp_f32_e32 v89, v89
	v_add_f32_e32 v215, 0, v82
	v_add_f32_e32 v215, v83, v215
	v_add_f32_e32 v215, v84, v215
	v_add_f32_e32 v215, v85, v215
	v_cvt_pk_bf16_f32 v82, v82, v83
	v_cvt_pk_bf16_f32 v83, v84, v85
	v_cvt_pk_bf16_f32 v84, v86, v87
	v_cvt_pk_bf16_f32 v85, v88, v89
	v_add_f32_e32 v215, v86, v215
	v_add_f32_e32 v215, v87, v215
	s_waitcnt lgkmcnt(1)
	v_mfma_f32_32x32x16_bf16 v[2:17], v[166:169], v[82:85], v[2:17]
	v_add_f32_e32 v215, v88, v215
	v_add_f32_e32 v215, v89, v215
	s_waitcnt lgkmcnt(0)
	v_mfma_f32_32x32x16_bf16 v[18:33], v[216:219], v[82:85], v[18:33]
	v_exp_f32_e32 v90, v90
	v_exp_f32_e32 v91, v91
	v_exp_f32_e32 v92, v92
	ds_read_b128 v[82:85], v165 offset:18464
	ds_read_b128 v[86:89], v165 offset:23072
	v_exp_f32_e32 v93, v93
	v_exp_f32_e32 v94, v94
	v_exp_f32_e32 v95, v95
	v_exp_f32_e32 v96, v96
	v_exp_f32_e32 v97, v97
	v_add_f32_e32 v166, v90, v215
	v_add_f32_e32 v166, v91, v166
	v_add_f32_e32 v166, v92, v166
	v_add_f32_e32 v166, v93, v166
	v_cvt_pk_bf16_f32 v90, v90, v91
	v_cvt_pk_bf16_f32 v91, v92, v93
	v_cvt_pk_bf16_f32 v92, v94, v95
	v_cvt_pk_bf16_f32 v93, v96, v97
	v_add_f32_e32 v166, v94, v166
	v_add_f32_e32 v166, v95, v166
	s_waitcnt lgkmcnt(1)
	v_mfma_f32_32x32x16_bf16 v[2:17], v[82:85], v[90:93], v[2:17]
	v_add_f32_e32 v166, v96, v166
	v_add_f32_e32 v166, v97, v166
	s_waitcnt lgkmcnt(0)
	v_mfma_f32_32x32x16_bf16 v[18:33], v[86:89], v[90:93], v[18:33]
	v_exp_f32_e32 v66, v66
	v_exp_f32_e32 v67, v67
	v_exp_f32_e32 v68, v68
	ds_read_b128 v[82:85], v165 offset:18496
	ds_read_b128 v[86:89], v165 offset:23104
	v_exp_f32_e32 v69, v69
	v_exp_f32_e32 v70, v70
	v_exp_f32_e32 v71, v71
	v_exp_f32_e32 v72, v72
	v_exp_f32_e32 v73, v73
	v_add_f32_e32 v90, v66, v166
	v_add_f32_e32 v90, v67, v90
	v_add_f32_e32 v90, v68, v90
	v_add_f32_e32 v90, v69, v90
	v_cvt_pk_bf16_f32 v66, v66, v67
	v_cvt_pk_bf16_f32 v67, v68, v69
	v_cvt_pk_bf16_f32 v68, v70, v71
	v_cvt_pk_bf16_f32 v69, v72, v73
	v_add_f32_e32 v90, v70, v90
	v_add_f32_e32 v90, v71, v90
	s_waitcnt lgkmcnt(1)
	v_mfma_f32_32x32x16_bf16 v[2:17], v[82:85], v[66:69], v[2:17]
	v_add_f32_e32 v90, v72, v90
	v_add_f32_e32 v90, v73, v90
	s_waitcnt lgkmcnt(0)
	v_mfma_f32_32x32x16_bf16 v[18:33], v[86:89], v[66:69], v[18:33]
	v_exp_f32_e32 v67, v74
	v_exp_f32_e32 v72, v75
	v_exp_f32_e32 v73, v76
	v_exp_f32_e32 v74, v77
	ds_read_b128 v[68:71], v165 offset:18528
	ds_read_b128 v[82:85], v165 offset:23136
	v_add_f32_e32 v66, v67, v90
	v_exp_f32_e32 v75, v78
	v_exp_f32_e32 v76, v79
	v_exp_f32_e32 v77, v80
	v_exp_f32_e32 v78, v81
	v_add_f32_e32 v66, v72, v66
	v_add_f32_e32 v66, v73, v66
	v_add_f32_e32 v66, v74, v66
	v_add_f32_e32 v66, v75, v66
	v_cvt_pk_bf16_f32 v72, v67, v72
	v_cvt_pk_bf16_f32 v73, v73, v74
	v_cvt_pk_bf16_f32 v74, v75, v76
	v_cvt_pk_bf16_f32 v75, v77, v78
	v_add_f32_e32 v66, v76, v66
	v_add_f32_e32 v66, v77, v66
	s_waitcnt lgkmcnt(1)
	v_mfma_f32_32x32x16_bf16 v[2:17], v[68:71], v[72:75], v[2:17]
	v_add_f32_e32 v66, v78, v66
	s_waitcnt lgkmcnt(0)
	v_mfma_f32_32x32x16_bf16 v[18:33], v[82:85], v[72:75], v[18:33]
	s_mov_b64 s[2:3], 0

; template <int MODE, bool MASK, bool WITH_O>
; DI void attn_tile_t(lptr Kt, lptr Vt, const bf16x8 (&qf)[4], f32x16& o0, f32x16& o1, RowState& rs, const TP& tp, int lane) {
;     ...
;     } else {
;         const int i = lane & 31;
;         lptr vp = Vt + i * KPB + hi * 16;
;         float sum = 0.f;
;     ...
;         PV_STEP(s0, 0, 0) PV_STEP(s0, 8, 32) PV_STEP(s1, 0, 64) PV_STEP(s1, 8, 96)
;     ...
;         rs.l += sum;
.LBB0_502:
	v_exp_f32_e32 v47, v76
	v_exp_f32_e32 v49, v72
	v_exp_f32_e32 v72, v75
	v_exp_f32_e32 v71, v71
	v_add_f32_e32 v48, 0, v47
	v_exp_f32_e32 v74, v74
	v_add_f32_e32 v48, v49, v48
	v_exp_f32_e32 v75, v70
	v_add3_u32 v77, s56, v135, v141
	v_add_f32_e32 v48, v72, v48
	v_exp_f32_e32 v73, v73
	ds_read_b128 v[58:61], v77 offset:18432
	ds_read_b128 v[62:65], v77 offset:23040
	v_add_f32_e32 v48, v71, v48
	v_exp_f32_e32 v69, v69
	v_add_f32_e32 v48, v74, v48
	v_add_f32_e32 v48, v75, v48
	v_add_f32_e32 v48, v73, v48
	v_add_f32_e32 v48, v69, v48
	v_cvt_pk_bf16_f32 v70, v47, v49
	v_cvt_pk_bf16_f32 v71, v72, v71
	v_cvt_pk_bf16_f32 v72, v74, v75
	v_cvt_pk_bf16_f32 v73, v73, v69
	s_waitcnt lgkmcnt(1)
	s_nop 0
	v_mfma_f32_32x32x16_bf16 v[2:17], v[58:61], v[70:73], v[2:17]
	s_waitcnt lgkmcnt(0)
	v_mfma_f32_32x32x16_bf16 v[18:33], v[62:65], v[70:73], v[18:33]
	v_exp_f32_e32 v47, v57
	v_exp_f32_e32 v49, v55
	v_exp_f32_e32 v55, v56
	v_exp_f32_e32 v45, v45
	v_add_f32_e32 v48, v47, v48
	v_exp_f32_e32 v46, v46
	v_add_f32_e32 v48, v49, v48
	v_exp_f32_e32 v56, v43
	v_add_f32_e32 v48, v55, v48
	v_add_f32_e32 v48, v45, v48
	v_add_f32_e32 v48, v46, v48
	v_add_f32_e32 v43, v56, v48
	v_exp_f32_e32 v48, v44
	ds_read_b128 v[58:61], v77 offset:18464
	ds_read_b128 v[62:65], v77 offset:23072
	v_exp_f32_e32 v57, v42
	v_cvt_pk_bf16_f32 v42, v47, v49
	v_add_f32_e32 v43, v48, v43
	v_cvt_pk_bf16_f32 v44, v46, v56
	v_add_f32_e32 v69, v57, v43
	v_cvt_pk_bf16_f32 v43, v55, v45
	v_cvt_pk_bf16_f32 v45, v48, v57
	s_waitcnt lgkmcnt(1)
	s_nop 0
	v_mfma_f32_32x32x16_bf16 v[2:17], v[58:61], v[42:45], v[2:17]
	s_waitcnt lgkmcnt(0)
	v_mfma_f32_32x32x16_bf16 v[18:33], v[62:65], v[42:45], v[18:33]
	v_exp_f32_e32 v55, v68
	v_exp_f32_e32 v57, v66
	v_exp_f32_e32 v58, v67
	v_exp_f32_e32 v53, v53
	v_add_f32_e32 v56, v55, v69
	v_exp_f32_e32 v54, v54
	v_add_f32_e32 v56, v57, v56
	v_exp_f32_e32 v59, v51
	v_add_f32_e32 v56, v58, v56
	v_add_f32_e32 v56, v53, v56
	v_add_f32_e32 v56, v54, v56
	v_add_f32_e32 v51, v59, v56
	v_exp_f32_e32 v56, v52
	ds_read_b128 v[42:45], v77 offset:18496
	ds_read_b128 v[46:49], v77 offset:23104
	v_exp_f32_e32 v60, v50
	v_cvt_pk_bf16_f32 v50, v55, v57
	v_add_f32_e32 v51, v56, v51
	v_cvt_pk_bf16_f32 v52, v54, v59
	v_add_f32_e32 v61, v60, v51
	v_cvt_pk_bf16_f32 v51, v58, v53
	v_cvt_pk_bf16_f32 v53, v56, v60
	s_waitcnt lgkmcnt(1)
	s_nop 0
	v_mfma_f32_32x32x16_bf16 v[2:17], v[42:45], v[50:53], v[2:17]
	s_waitcnt lgkmcnt(0)
	v_mfma_f32_32x32x16_bf16 v[18:33], v[46:49], v[50:53], v[18:33]
	v_exp_f32_e32 v41, v41
	v_exp_f32_e32 v38, v38
	v_exp_f32_e32 v40, v40
	v_exp_f32_e32 v36, v36
	v_add_f32_e32 v50, v41, v61
	v_exp_f32_e32 v39, v39
	v_add_f32_e32 v50, v38, v50
	v_exp_f32_e32 v51, v35
	v_add_f32_e32 v50, v40, v50
	v_add_f32_e32 v50, v36, v50
	v_add_f32_e32 v50, v39, v50
	v_exp_f32_e32 v37, v37
	ds_read_b128 v[42:45], v77 offset:18528
	ds_read_b128 v[46:49], v77 offset:23136
	v_add_f32_e32 v35, v51, v50
	v_exp_f32_e32 v50, v34
	v_add_f32_e32 v35, v37, v35
	v_cvt_pk_bf16_f32 v34, v41, v38
	v_add_f32_e32 v66, v50, v35
	v_cvt_pk_bf16_f32 v35, v40, v36
	v_cvt_pk_bf16_f32 v36, v39, v51
	v_cvt_pk_bf16_f32 v37, v37, v50
	s_waitcnt lgkmcnt(1)
	s_nop 0
	v_mfma_f32_32x32x16_bf16 v[2:17], v[42:45], v[34:37], v[2:17]
	s_waitcnt lgkmcnt(0)
	v_mfma_f32_32x32x16_bf16 v[18:33], v[46:49], v[34:37], v[18:33]
	v_mov_b32_e32 v164, v159
	v_mov_b32_e32 v163, v160

; DI float exp2_fast(float x) { return __builtin_amdgcn_exp2f(x); }
; template <int MODE, bool MASK, bool WITH_O>
; DI void attn_tile_t(lptr Kt, lptr Vt, const bf16x8 (&qf)[4], f32x16& o0, f32x16& o1, RowState& rs, const TP& tp, int lane) {
;     ...
;     if (__builtin_expect(__any(trig), 0)) {
;         asm volatile("" ::: "memory");
;         const float d = trig ? mx : 0.f; rs.mref += d;
;         const float al = was ? exp2_fast(-d) : 1.f; rs.l *= al;
;         if (WITH_O) { o0 = o0 * al; o1 = o1 * al; }
; #pragma unroll
;         for (int r = 0; r < 16; ++r) { s0[r] -= d; s1[r] -= d; }
.LBB0_508:
	v_mov_b32_e32 v163, v160
	s_andn2_b64 vcc, exec, s[0:1]
	s_cbranch_vccnz .LBB0_512
.LBB0_509:
	s_xor_b32 s2, s55, 1
	s_mul_i32 s0, s2, 0x2400
	v_add_u32_e32 v34, s0, v127
	s_waitcnt vmcnt(1)
	ds_write_b128 v34, v[114:117]
	s_waitcnt vmcnt(0)
	ds_write_b128 v34, v[118:121] offset:18432
	s_mov_b64 s[0:1], exec
	v_readlane_b32 s26, v250, 19
	v_readlane_b32 s27, v250, 20
	s_and_b64 s[26:27], s[0:1], s[26:27]
	s_mov_b64 exec, s[26:27]
	v_lshl_add_u32 v34, s2, 8, v129
	ds_write_b32 v34, v149 offset:36864
	s_or_b64 exec, exec, s[0:1]
.LBB0_512:
	s_add_i32 s54, s54, 1
	s_add_i32 s31, s31, 64
	s_add_i32 s0, s53, s54
	s_cmp_lg_u32 s0, 0
	v_subrev_u32_e32 v158, 64, v158
	s_waitcnt lgkmcnt(0)
	s_barrier
	s_cbranch_scc0 .Lfox_exit
	v_mov_b32_e32 v160, v163
	s_branch .LBB0_490
.LBB0_514:
	v_cndmask_b32_e64 v166, 0, v165, s[28:29]
	v_exp_f32_e64 v34, -v166
	v_add_f32_e32 v163, v160, v166
	v_pk_add_f32 v[82:83], v[82:83], v[166:167] op_sel_hi:[1,0] neg_lo:[0,1] neg_hi:[0,1]
	v_cndmask_b32_e64 v34, 1.0, v34, s[22:23]
	v_mul_f32_e32 v164, v159, v34
	v_pk_mul_f32 v[16:17], v[16:17], v[34:35] op_sel_hi:[1,0]
	v_pk_mul_f32 v[14:15], v[14:15], v[34:35] op_sel_hi:[1,0]
	v_pk_mul_f32 v[12:13], v[12:13], v[34:35] op_sel_hi:[1,0]
	v_pk_mul_f32 v[10:11], v[10:11], v[34:35] op_sel_hi:[1,0]
	v_pk_mul_f32 v[8:9], v[8:9], v[34:35] op_sel_hi:[1,0]
	v_pk_mul_f32 v[6:7], v[6:7], v[34:35] op_sel_hi:[1,0]
	v_pk_mul_f32 v[4:5], v[4:5], v[34:35] op_sel_hi:[1,0]
	v_pk_mul_f32 v[2:3], v[2:3], v[34:35] op_sel_hi:[1,0]
	v_pk_mul_f32 v[32:33], v[32:33], v[34:35] op_sel_hi:[1,0]
	v_pk_mul_f32 v[30:31], v[30:31], v[34:35] op_sel_hi:[1,0]
	v_pk_mul_f32 v[28:29], v[28:29], v[34:35] op_sel_hi:[1,0]
	v_pk_mul_f32 v[26:27], v[26:27], v[34:35] op_sel_hi:[1,0]
	v_pk_mul_f32 v[24:25], v[24:25], v[34:35] op_sel_hi:[1,0]
	v_pk_mul_f32 v[22:23], v[22:23], v[34:35] op_sel_hi:[1,0]
	v_pk_mul_f32 v[20:21], v[20:21], v[34:35] op_sel_hi:[1,0]
	v_pk_mul_f32 v[18:19], v[18:19], v[34:35] op_sel_hi:[1,0]
	v_pk_add_f32 v[66:67], v[66:67], v[166:167] op_sel_hi:[1,0] neg_lo:[0,1] neg_hi:[0,1]
	v_pk_add_f32 v[84:85], v[84:85], v[166:167] op_sel_hi:[1,0] neg_lo:[0,1] neg_hi:[0,1]
	v_pk_add_f32 v[68:69], v[68:69], v[166:167] op_sel_hi:[1,0] neg_lo:[0,1] neg_hi:[0,1]
	v_pk_add_f32 v[86:87], v[86:87], v[166:167] op_sel_hi:[1,0] neg_lo:[0,1] neg_hi:[0,1]
	v_pk_add_f32 v[70:71], v[70:71], v[166:167] op_sel_hi:[1,0] neg_lo:[0,1] neg_hi:[0,1]
	v_pk_add_f32 v[88:89], v[88:89], v[166:167] op_sel_hi:[1,0] neg_lo:[0,1] neg_hi:[0,1]
	v_pk_add_f32 v[72:73], v[72:73], v[166:167] op_sel_hi:[1,0] neg_lo:[0,1] neg_hi:[0,1]
	v_pk_add_f32 v[90:91], v[90:91], v[166:167] op_sel_hi:[1,0] neg_lo:[0,1] neg_hi:[0,1]
	v_pk_add_f32 v[74:75], v[74:75], v[166:167] op_sel_hi:[1,0] neg_lo:[0,1] neg_hi:[0,1]
	v_pk_add_f32 v[92:93], v[92:93], v[166:167] op_sel_hi:[1,0] neg_lo:[0,1] neg_hi:[0,1]
	v_pk_add_f32 v[76:77], v[76:77], v[166:167] op_sel_hi:[1,0] neg_lo:[0,1] neg_hi:[0,1]
	v_pk_add_f32 v[94:95], v[94:95], v[166:167] op_sel_hi:[1,0] neg_lo:[0,1] neg_hi:[0,1]
	v_pk_add_f32 v[78:79], v[78:79], v[166:167] op_sel_hi:[1,0] neg_lo:[0,1] neg_hi:[0,1]
	v_pk_add_f32 v[96:97], v[96:97], v[166:167] op_sel_hi:[1,0] neg_lo:[0,1] neg_hi:[0,1]
	v_pk_add_f32 v[80:81], v[80:81], v[166:167] op_sel_hi:[1,0] neg_lo:[0,1] neg_hi:[0,1]
	s_branch .LBB0_497

; #define ATT_LOOP_END(NT, HASCS) } \
;       if (jt_ + 1 < (NT)) { tile_lstore(L + AL_K + (cur_ ^ 1) * TILE_B, L + AL_V + (cur_ ^ 1) * TILE_B, kr_, vr_, tid); if (HASCS && tid < 64) ((LAS float*)(L + AL_CS))[(cur_ ^ 1) * 64 + tid] = csr_; } \
;       __syncthreads(); } }
; DI void fox_unit(const Params& P, lptr L, int u, int tid, int lane, int wid) {
;     ...
;     ATT_LOOP_END(NT, true)
;     float l = rs.l; l += __shfl_xor(l, 32);
;     const float inv = 1.f / fmaxf(l, 1e-30f);
;     store_o_bf16(ATT + (size_t)(b * SEQ + t) * DM + h * 64, o0, o1, inv, hi);
.Lfox_exit:
	v_mov_b64_e32 v[34:35], v[2:3]
	v_mov_b64_e32 v[36:37], v[4:5]
	v_mov_b64_e32 v[38:39], v[6:7]
	v_mov_b64_e32 v[40:41], v[8:9]
	v_mov_b64_e32 v[42:43], v[10:11]
	v_mov_b64_e32 v[44:45], v[12:13]
	v_mov_b64_e32 v[46:47], v[14:15]
	v_mov_b64_e32 v[48:49], v[16:17]
	v_mov_b64_e32 v[50:51], v[18:19]
	v_mov_b64_e32 v[52:53], v[20:21]
	v_mov_b64_e32 v[54:55], v[22:23]
	v_mov_b64_e32 v[56:57], v[24:25]
	v_mov_b64_e32 v[58:59], v[26:27]
	v_mov_b64_e32 v[60:61], v[28:29]
	v_mov_b64_e32 v[62:63], v[30:31]
	v_mov_b64_e32 v[64:65], v[32:33]
	s_branch .LBB0_517

; #define PG8_STAGE(bufoff, gbase, voff) do { _Pragma("unroll") for (int _i = 0; _i < 2; ++_i) \
;         __builtin_amdgcn_global_load_lds((const unsigned*)((const char*)(gbase) + (voff)[_i]), (PG8_LAS unsigned*)(lds + (bufoff) + ldsw + _i * 8192), 16, 0, 0); } while (0)
; #define PG8_WAIT_V(n) asm volatile("s_waitcnt vmcnt(" #n ")" ::: "memory")
; #define PG8_BAR __builtin_amdgcn_s_barrier()
; template <class Epi, class Sched, bool ALIGN_EPI = false, bool SP2 = false>
; __device__ __forceinline__ void gemm_phase(PG8_LAS unsigned char* lds, const Gemm g, const Sched& S, const Epi& E) {
;     ...
;     const char* cA = PG8_UA(cur); const char* cB = PG8_UB(cur);
;     S.a_ready(cur);
;     if constexpr (SP2) {
;         PG8_STAGE(PG8_SB(0, 0), cB, voffB); PG8_STAGE(PG8_SB(0, 1), cB + hstepB, voffB); PG8_STAGE(PG8_SA(0, 0), cA, voffA); PG8_STAGE(PG8_SA(0, 1), cA + hstepA, voffA);
;         if (wr == 1) PG8_BAR;
;         PG8_WAIT_V(2); PG8_BAR;
;         PG8_STAGE(PG8_SB(1, 0), cB + kstep, voffB); PG8_STAGE(PG8_SA(1, 0), cA + kstep, voffA); PG8_STAGE(PG8_SB(1, 1), cB + hstepB + kstep, voffB);
;         PG8_WAIT_V(6); PG8_BAR;
;     } else {
;         PG8_STAGE(PG8_SB(0, 0), cB, voffB); PG8_STAGE(PG8_SA(0, 0), cA, voffA); PG8_STAGE(PG8_SB(0, 1), cB + hstepB, voffB); PG8_STAGE(PG8_SA(0, 1), cA + hstepA, voffA);
;         if (wr == 1) PG8_BAR;
;         PG8_WAIT_V(4); PG8_BAR;
;         PG8_STAGE(PG8_SB(1, 0), cB + kstep, voffB); PG8_STAGE(PG8_SA(1, 0), cA + kstep, voffA); PG8_STAGE(PG8_SB(1, 1), cB + hstepB + kstep, voffB);
;         PG8_WAIT_V(6); PG8_BAR;
;     }
;     __device__ __forceinline__ void operator()(const f32x4 (&acc)[2][2][4][2], const Unit& u, int wr, int wc, int fr, int fq) const {
;     ...
;             const int hc = (u.pn * BM + colt) >> 1; const float r = 1.f / sqrtf(rstd[row] * (1.f / DM) + RMS_EPS);
.LBB0_1043:
	s_add_u32 s10, s34, 0x7800000
	s_addc_u32 s11, s35, 0
	s_add_u32 s12, s34, 0x3420000
	s_addc_u32 s13, s35, 0
	s_lshl_b32 s4, s4, 5
	s_mov_b64 s[14:15], 0x80
	s_and_b32 s18, s4, 0x60
	s_add_i32 m0, s42, 0x18000
	v_lshl_add_u64 v[6:7], v[6:7], 0, s[14:15]
	s_lshl_b32 s1, s3, 13
	s_lshl_b32 s16, s18, 7
	s_waitcnt vmcnt(2)
	s_barrier
	global_load_lds_dwordx4 v[6:7], off
	v_lshl_add_u64 v[4:5], v[4:5], 0, s[14:15]
	s_add_i32 m0, s42, 0x1a000
	s_add_i32 s47, s42, 0x8000
	s_add_i32 s48, s42, 0xa000
	global_load_lds_dwordx4 v[4:5], off
	v_lshl_add_u64 v[0:1], v[0:1], 0, s[14:15]
	s_mov_b32 m0, s47
	s_add_u32 s4, s26, 0x40080
	global_load_lds_dwordx4 v[0:1], off
	v_lshl_add_u64 v[0:1], v[2:3], 0, s[14:15]
	s_mov_b32 m0, s48
	s_addc_u32 s5, s27, 0
	global_load_lds_dwordx4 v[0:1], off
	s_add_i32 m0, s42, 0x1c000
	v_lshl_add_u64 v[0:1], s[4:5], 0, v[132:133]
	global_load_lds_dwordx4 v[0:1], off
	v_lshl_add_u64 v[0:1], s[4:5], 0, v[128:129]
	s_add_i32 m0, s42, 0x1e000
	v_lshlrev_b32_e32 v2, 2, v194
	global_load_lds_dwordx4 v[0:1], off
	v_and_b32_e32 v0, 15, v194
	v_lshlrev_b32_e32 v1, 1, v11
	v_lshl_or_b32 v146, s3, 6, v0
	v_lshl_or_b32 v0, v0, 6, v1
	v_and_b32_e32 v2, 32, v2
	v_bitop3_b32 v0, v0, s1, v2 bitop3:0xde
	v_lshlrev_b32_e32 v3, 6, v194
	s_movk_i32 s1, 0x3c0
	v_and_or_b32 v1, v3, s1, v1
	v_bitop3_b32 v147, s16, v1, v2 bitop3:0xf6
	v_lshlrev_b32_e32 v1, 8, v194
	v_and_b32_e32 v1, 0x38000, v1
	v_lshlrev_b32_e32 v2, 11, v12
	v_or3_b32 v1, v9, v1, v2
	v_add_u32_e32 v136, v1, v10
	v_lshlrev_b32_e32 v1, 4, v8
	s_waitcnt vmcnt(6)
	s_cmpk_lt_u32 s2, 0x100
	v_and_b32_e32 v1, 0x78000, v1
	s_cselect_b64 s[16:17], -1, 0
	v_readlane_b32 s2, v251, 13
	v_or3_b32 v1, v9, v1, v2
	s_add_i32 s51, 0, 0x10000
	s_add_i32 s52, 0, 0x14000
	s_ashr_i32 s49, s2, 31
	s_mov_b32 s50, s2
	v_or_b32_e32 v148, s18, v11
	v_mov_b32_e32 v137, v133
	v_add_u32_e32 v138, v1, v10
	v_mov_b32_e32 v139, v133
	v_mov_b64_e32 v[140:141], 0xb00
	v_mov_b64_e32 v[142:143], 0xaff
	s_waitcnt vmcnt(0)
	v_add_u32_e32 v149, s51, v147
	v_add_u32_e32 v150, s52, v147
	v_add_u32_e32 v151, 0, v0
	v_mov_b32_e32 v152, 0x358637bd
	s_mov_b32 s53, 0xf800000
	v_mov_b32_e32 v153, 0x260
	s_movk_i32 s54, 0x1680
	v_lshl_add_u32 v246, s0, 8, v146
	v_mov_b32_e32 v247, 0
	v_lshl_add_u64 v[246:247], v[246:247], 2, s[12:13]
	global_load_dword v238, v[246:247], off
	global_load_dword v239, v[246:247], off offset:64
	global_load_dword v240, v[246:247], off offset:128
	global_load_dword v241, v[246:247], off offset:192
	global_load_dword v242, v[246:247], off offset:512
	global_load_dword v243, v[246:247], off offset:576
	global_load_dword v244, v[246:247], off offset:640
	global_load_dword v245, v[246:247], off offset:704
	s_barrier
	v_readlane_b32 s3, v251, 14
	s_branch .LBB0_1046

; __device__ __forceinline__ unsigned cvt_pk_bf16(float lo, float hi) { return pk_bf16(lo, hi); }
; __device__ __forceinline__ float silu_f(float x) { return x * __builtin_amdgcn_rcpf(1.f + __builtin_amdgcn_exp2f(-x * L2E)); }
;     __device__ __forceinline__ void operator()(const f32x4 (&acc)[2][2][4][2], const Unit& u, int wr, int wc, int fr, int fq) const {
;         EPI_ROWS_BEGIN
;             const int hc = (u.pn * BM + colt) >> 1; const float r = 1.f / sqrtf(rstd[row] * (1.f / DM) + RMS_EPS);
;             const float h0 = silu_f(v0[0] * r) * (v0[1] * r), h1 = silu_f(v0[2] * r) * (v0[3] * r), h2 = silu_f(v1[0] * r) * (v1[1] * r), h3 = silu_f(v1[2] * r) * (v1[3] * r);
;             u32x2 w; w.x = cvt_pk_bf16(h0, h1); w.y = cvt_pk_bf16(h2, h3);
;             *(u32x2*)(hid + (size_t)row * HIDLD + hc) = w;
;         EPI_ROWS_END
.LBB0_1052:
	v_mov_b32_e32 v230, v238
	v_mov_b32_e32 v231, v239
	v_mov_b32_e32 v232, v240
	v_mov_b32_e32 v233, v241
	v_mov_b32_e32 v234, v242
	v_mov_b32_e32 v235, v243
	v_mov_b32_e32 v236, v244
	v_mov_b32_e32 v237, v245
	v_lshl_add_u32 v246, s18, 8, v146
	v_mov_b32_e32 v247, 0
	v_lshl_add_u64 v[246:247], v[246:247], 2, s[12:13]
	global_load_dword v238, v[246:247], off
	global_load_dword v239, v[246:247], off offset:64
	global_load_dword v240, v[246:247], off offset:128
	global_load_dword v241, v[246:247], off offset:192
	global_load_dword v242, v[246:247], off offset:512
	global_load_dword v243, v[246:247], off offset:576
	global_load_dword v244, v[246:247], off offset:640
	global_load_dword v245, v[246:247], off offset:704
	v_lshl_add_u32 v144, s0, 8, v146
	s_mov_b32 s98, 0x16800
	s_mov_b32 s99, 0
	v_mov_b64_e32 v[212:213], s[10:11]
	v_lshl_or_b32 v214, s56, 8, v148
	v_mov_b32_e32 v215, 0
	v_mad_u64_u32 v[196:197], vcc, v144, s54, v[212:213]
	v_lshl_add_u64 v[196:197], v[196:197], 0, v[214:215]
	v_lshl_add_u64 v[198:199], v[196:197], 0, s[98:99]
	v_lshl_add_u64 v[204:205], s[98:99], 3, v[196:197]
	v_lshl_add_u64 v[200:201], v[198:199], 0, s[98:99]
	v_lshl_add_u64 v[206:207], v[204:205], 0, s[98:99]
	v_lshl_add_u64 v[202:203], v[200:201], 0, s[98:99]
	v_lshl_add_u64 v[208:209], v[206:207], 0, s[98:99]
	v_lshl_add_u64 v[210:211], v[208:209], 0, s[98:99]
	v_fmamk_f32 v230, v230, 0x3a800000, v152
	v_fmamk_f32 v231, v231, 0x3a800000, v152
	v_fmamk_f32 v232, v232, 0x3a800000, v152
	v_fmamk_f32 v233, v233, 0x3a800000, v152
	v_fmamk_f32 v234, v234, 0x3a800000, v152
	v_fmamk_f32 v235, v235, 0x3a800000, v152
	v_fmamk_f32 v236, v236, 0x3a800000, v152
	v_fmamk_f32 v237, v237, 0x3a800000, v152
	v_rsq_f32_e32 v164, v230
	v_rsq_f32_e32 v165, v231
	v_rsq_f32_e32 v166, v232
	v_rsq_f32_e32 v167, v233
	v_rsq_f32_e32 v168, v234
	v_rsq_f32_e32 v169, v235
	v_rsq_f32_e32 v170, v236
	v_rsq_f32_e32 v171, v237
	v_mul_f32_e32 v172, v230, v164
	v_mul_f32_e32 v173, v231, v165
	v_mul_f32_e32 v174, v232, v166
	v_mul_f32_e32 v175, v233, v167
	v_mul_f32_e32 v176, v234, v168
	v_mul_f32_e32 v177, v235, v169
	v_mul_f32_e32 v178, v236, v170
	v_mul_f32_e32 v179, v237, v171
	v_fma_f32 v172, -v172, v164, 1.0
	v_fma_f32 v173, -v173, v165, 1.0
	v_fma_f32 v174, -v174, v166, 1.0
	v_fma_f32 v175, -v175, v167, 1.0
	v_fma_f32 v176, -v176, v168, 1.0
	v_fma_f32 v177, -v177, v169, 1.0
	v_fma_f32 v178, -v178, v170, 1.0
	v_fma_f32 v179, -v179, v171, 1.0
	v_mul_f32_e32 v180, 0.5, v164
	v_mul_f32_e32 v181, 0.5, v165
	v_mul_f32_e32 v182, 0.5, v166
	v_mul_f32_e32 v183, 0.5, v167
	v_mul_f32_e32 v184, 0.5, v168
	v_mul_f32_e32 v185, 0.5, v169
	v_mul_f32_e32 v186, 0.5, v170
	v_mul_f32_e32 v187, 0.5, v171
	v_fma_f32 v164, v180, v172, v164
	v_fma_f32 v165, v181, v173, v165
	v_fma_f32 v166, v182, v174, v166
	v_fma_f32 v167, v183, v175, v167
	v_fma_f32 v168, v184, v176, v168
	v_fma_f32 v169, v185, v177, v169
	v_fma_f32 v170, v186, v178, v170
	v_fma_f32 v171, v187, v179, v171
	v_mul_f32_e32 v172, 0xbfb8aa3b, v164
	v_mul_f32_e32 v173, 0xbfb8aa3b, v165
	v_mul_f32_e32 v174, 0xbfb8aa3b, v166
	v_mul_f32_e32 v175, 0xbfb8aa3b, v167
	v_mul_f32_e32 v176, 0xbfb8aa3b, v168
	v_mul_f32_e32 v177, 0xbfb8aa3b, v169
	v_mul_f32_e32 v178, 0xbfb8aa3b, v170
	v_mul_f32_e32 v179, 0xbfb8aa3b, v171
	v_mul_f32_e32 v216, v124, v172
	v_mul_f32_e32 v217, v126, v172
	v_mul_f32_e32 v218, v120, v172
	v_mul_f32_e32 v219, v122, v172
	v_mul_f32_e32 v124, v124, v125
	v_mul_f32_e32 v126, v126, v127
	v_mul_f32_e32 v120, v120, v121
	v_mul_f32_e32 v122, v122, v123
	v_exp_f32_e32 v216, v216
	v_exp_f32_e32 v217, v217
	v_exp_f32_e32 v218, v218
	v_exp_f32_e32 v219, v219
	v_fma_f32 v216, v216, v230, v230
	v_fma_f32 v217, v217, v230, v230
	v_fma_f32 v218, v218, v230, v230
	v_fma_f32 v219, v219, v230, v230
	v_rcp_f32_e32 v216, v216
	v_rcp_f32_e32 v217, v217
	v_rcp_f32_e32 v218, v218
	v_rcp_f32_e32 v219, v219
	v_mul_f32_e32 v124, v124, v216
	v_mul_f32_e32 v126, v126, v217
	v_mul_f32_e32 v120, v120, v218
	v_mul_f32_e32 v122, v122, v219
	v_cvt_pk_bf16_f32 v124, v124, v126
	v_cvt_pk_bf16_f32 v125, v120, v122
	global_store_dwordx2 v[196:197], v[124:125], off
	v_mul_f32_e32 v220, v116, v172
	v_mul_f32_e32 v221, v118, v172
	v_mul_f32_e32 v222, v112, v172
	v_mul_f32_e32 v223, v114, v172
	v_mul_f32_e32 v116, v116, v117
	v_mul_f32_e32 v118, v118, v119
	v_mul_f32_e32 v112, v112, v113
	v_mul_f32_e32 v114, v114, v115
	v_exp_f32_e32 v220, v220
	v_exp_f32_e32 v221, v221
	v_exp_f32_e32 v222, v222
	v_exp_f32_e32 v223, v223
	v_fma_f32 v220, v220, v230, v230
	v_fma_f32 v221, v221, v230, v230
	v_fma_f32 v222, v222, v230, v230
	v_fma_f32 v223, v223, v230, v230
	v_rcp_f32_e32 v220, v220
	v_rcp_f32_e32 v221, v221
	v_rcp_f32_e32 v222, v222
	v_rcp_f32_e32 v223, v223
	v_mul_f32_e32 v116, v116, v220
	v_mul_f32_e32 v118, v118, v221
	v_mul_f32_e32 v112, v112, v222
	v_mul_f32_e32 v114, v114, v223
	v_cvt_pk_bf16_f32 v116, v116, v118
	v_cvt_pk_bf16_f32 v117, v112, v114
	global_store_dwordx2 v[196:197], v[116:117], off offset:128
	v_mul_f32_e32 v216, v108, v173
	v_mul_f32_e32 v217, v110, v173
	v_mul_f32_e32 v218, v104, v173
	v_mul_f32_e32 v219, v106, v173
	v_mul_f32_e32 v108, v108, v109
	v_mul_f32_e32 v110, v110, v111
	v_mul_f32_e32 v104, v104, v105
	v_mul_f32_e32 v106, v106, v107
	v_exp_f32_e32 v216, v216
	v_exp_f32_e32 v217, v217
	v_exp_f32_e32 v218, v218
	v_exp_f32_e32 v219, v219
	v_fma_f32 v216, v216, v231, v231
	v_fma_f32 v217, v217, v231, v231
	v_fma_f32 v218, v218, v231, v231
	v_fma_f32 v219, v219, v231, v231
	v_rcp_f32_e32 v216, v216
	v_rcp_f32_e32 v217, v217
	v_rcp_f32_e32 v218, v218
	v_rcp_f32_e32 v219, v219
	v_mul_f32_e32 v108, v108, v216
	v_mul_f32_e32 v110, v110, v217
; __device__ __forceinline__ unsigned cvt_pk_bf16(float lo, float hi) { return pk_bf16(lo, hi); }
; __device__ __forceinline__ float silu_f(float x) { return x * __builtin_amdgcn_rcpf(1.f + __builtin_amdgcn_exp2f(-x * L2E)); }
;     __device__ __forceinline__ void operator()(const f32x4 (&acc)[2][2][4][2], const Unit& u, int wr, int wc, int fr, int fq) const {
;         EPI_ROWS_BEGIN
;             const int hc = (u.pn * BM + colt) >> 1; const float r = 1.f / sqrtf(rstd[row] * (1.f / DM) + RMS_EPS);
;             const float h0 = silu_f(v0[0] * r) * (v0[1] * r), h1 = silu_f(v0[2] * r) * (v0[3] * r), h2 = silu_f(v1[0] * r) * (v1[1] * r), h3 = silu_f(v1[2] * r) * (v1[3] * r);
;             u32x2 w; w.x = cvt_pk_bf16(h0, h1); w.y = cvt_pk_bf16(h2, h3);
;             *(u32x2*)(hid + (size_t)row * HIDLD + hc) = w;
;         EPI_ROWS_END
	v_mul_f32_e32 v104, v104, v218
	v_mul_f32_e32 v106, v106, v219
	v_cvt_pk_bf16_f32 v108, v108, v110
	v_cvt_pk_bf16_f32 v109, v104, v106
	global_store_dwordx2 v[198:199], v[108:109], off
	v_mul_f32_e32 v220, v100, v173
	v_mul_f32_e32 v221, v102, v173
	v_mul_f32_e32 v222, v96, v173
	v_mul_f32_e32 v223, v98, v173
	v_mul_f32_e32 v100, v100, v101
	v_mul_f32_e32 v102, v102, v103
	v_mul_f32_e32 v96, v96, v97
	v_mul_f32_e32 v98, v98, v99
	v_exp_f32_e32 v220, v220
	v_exp_f32_e32 v221, v221
	v_exp_f32_e32 v222, v222
	v_exp_f32_e32 v223, v223
	v_fma_f32 v220, v220, v231, v231
	v_fma_f32 v221, v221, v231, v231
	v_fma_f32 v222, v222, v231, v231
	v_fma_f32 v223, v223, v231, v231
	v_rcp_f32_e32 v220, v220
	v_rcp_f32_e32 v221, v221
	v_rcp_f32_e32 v222, v222
	v_rcp_f32_e32 v223, v223
	v_mul_f32_e32 v100, v100, v220
	v_mul_f32_e32 v102, v102, v221
	v_mul_f32_e32 v96, v96, v222
	v_mul_f32_e32 v98, v98, v223
	v_cvt_pk_bf16_f32 v100, v100, v102
	v_cvt_pk_bf16_f32 v101, v96, v98
	global_store_dwordx2 v[198:199], v[100:101], off offset:128
	v_mul_f32_e32 v216, v92, v174
	v_mul_f32_e32 v217, v94, v174
	v_mul_f32_e32 v218, v88, v174
	v_mul_f32_e32 v219, v90, v174
	v_mul_f32_e32 v92, v92, v93
	v_mul_f32_e32 v94, v94, v95
	v_mul_f32_e32 v88, v88, v89
	v_mul_f32_e32 v90, v90, v91
	v_exp_f32_e32 v216, v216
	v_exp_f32_e32 v217, v217
	v_exp_f32_e32 v218, v218
	v_exp_f32_e32 v219, v219
	v_fma_f32 v216, v216, v232, v232
	v_fma_f32 v217, v217, v232, v232
	v_fma_f32 v218, v218, v232, v232
	v_fma_f32 v219, v219, v232, v232
	v_rcp_f32_e32 v216, v216
	v_rcp_f32_e32 v217, v217
	v_rcp_f32_e32 v218, v218
	v_rcp_f32_e32 v219, v219
	v_mul_f32_e32 v92, v92, v216
	v_mul_f32_e32 v94, v94, v217
	v_mul_f32_e32 v88, v88, v218
	v_mul_f32_e32 v90, v90, v219
	v_cvt_pk_bf16_f32 v92, v92, v94
	v_cvt_pk_bf16_f32 v93, v88, v90
	global_store_dwordx2 v[200:201], v[92:93], off
	v_mul_f32_e32 v220, v84, v174
	v_mul_f32_e32 v221, v86, v174
	v_mul_f32_e32 v222, v80, v174
	v_mul_f32_e32 v223, v82, v174
	v_mul_f32_e32 v84, v84, v85
	v_mul_f32_e32 v86, v86, v87
	v_mul_f32_e32 v80, v80, v81
	v_mul_f32_e32 v82, v82, v83
	v_exp_f32_e32 v220, v220
	v_exp_f32_e32 v221, v221
	v_exp_f32_e32 v222, v222
	v_exp_f32_e32 v223, v223
	v_fma_f32 v220, v220, v232, v232
	v_fma_f32 v221, v221, v232, v232
	v_fma_f32 v222, v222, v232, v232
	v_fma_f32 v223, v223, v232, v232
	v_rcp_f32_e32 v220, v220
	v_rcp_f32_e32 v221, v221
	v_rcp_f32_e32 v222, v222
	v_rcp_f32_e32 v223, v223
	v_mul_f32_e32 v84, v84, v220
	v_mul_f32_e32 v86, v86, v221
	v_mul_f32_e32 v80, v80, v222
	v_mul_f32_e32 v82, v82, v223
	v_cvt_pk_bf16_f32 v84, v84, v86
	v_cvt_pk_bf16_f32 v85, v80, v82
	global_store_dwordx2 v[200:201], v[84:85], off offset:128
	v_mul_f32_e32 v216, v76, v175
	v_mul_f32_e32 v217, v78, v175
	v_mul_f32_e32 v218, v72, v175
	v_mul_f32_e32 v219, v74, v175
	v_mul_f32_e32 v76, v76, v77
	v_mul_f32_e32 v78, v78, v79
	v_mul_f32_e32 v72, v72, v73
	v_mul_f32_e32 v74, v74, v75
	v_exp_f32_e32 v216, v216
	v_exp_f32_e32 v217, v217
	v_exp_f32_e32 v218, v218
	v_exp_f32_e32 v219, v219
	v_fma_f32 v216, v216, v233, v233
	v_fma_f32 v217, v217, v233, v233
	v_fma_f32 v218, v218, v233, v233
	v_fma_f32 v219, v219, v233, v233
	v_rcp_f32_e32 v216, v216
	v_rcp_f32_e32 v217, v217
	v_rcp_f32_e32 v218, v218
	v_rcp_f32_e32 v219, v219
	v_mul_f32_e32 v76, v76, v216
	v_mul_f32_e32 v78, v78, v217
	v_mul_f32_e32 v72, v72, v218
	v_mul_f32_e32 v74, v74, v219
	v_cvt_pk_bf16_f32 v76, v76, v78
	v_cvt_pk_bf16_f32 v77, v72, v74
	global_store_dwordx2 v[202:203], v[76:77], off
	v_mul_f32_e32 v220, v68, v175
	v_mul_f32_e32 v221, v70, v175
	v_mul_f32_e32 v222, v64, v175
	v_mul_f32_e32 v223, v66, v175
	v_mul_f32_e32 v68, v68, v69
	v_mul_f32_e32 v70, v70, v71
	v_mul_f32_e32 v64, v64, v65
	v_mul_f32_e32 v66, v66, v67
	v_exp_f32_e32 v220, v220
	v_exp_f32_e32 v221, v221
	v_exp_f32_e32 v222, v222
	v_exp_f32_e32 v223, v223
	v_fma_f32 v220, v220, v233, v233
	v_fma_f32 v221, v221, v233, v233
	v_fma_f32 v222, v222, v233, v233
	v_fma_f32 v223, v223, v233, v233
	v_rcp_f32_e32 v220, v220
	v_rcp_f32_e32 v221, v221
	v_rcp_f32_e32 v222, v222
	v_rcp_f32_e32 v223, v223
	v_mul_f32_e32 v68, v68, v220
	v_mul_f32_e32 v70, v70, v221
	v_mul_f32_e32 v64, v64, v222
	v_mul_f32_e32 v66, v66, v223
	v_cvt_pk_bf16_f32 v68, v68, v70
	v_cvt_pk_bf16_f32 v69, v64, v66
	global_store_dwordx2 v[202:203], v[68:69], off offset:128
	v_mul_f32_e32 v216, v60, v176
	v_mul_f32_e32 v217, v62, v176
	v_mul_f32_e32 v218, v56, v176
	v_mul_f32_e32 v219, v58, v176
	v_mul_f32_e32 v60, v60, v61
	v_mul_f32_e32 v62, v62, v63
	v_mul_f32_e32 v56, v56, v57
	v_mul_f32_e32 v58, v58, v59
	v_exp_f32_e32 v216, v216
	v_exp_f32_e32 v217, v217
	v_exp_f32_e32 v218, v218
	v_exp_f32_e32 v219, v219
	v_fma_f32 v216, v216, v234, v234
	v_fma_f32 v217, v217, v234, v234
	v_fma_f32 v218, v218, v234, v234
	v_fma_f32 v219, v219, v234, v234
	v_rcp_f32_e32 v216, v216
	v_rcp_f32_e32 v217, v217
	v_rcp_f32_e32 v218, v218
	v_rcp_f32_e32 v219, v219
	v_mul_f32_e32 v60, v60, v216
	v_mul_f32_e32 v62, v62, v217
	v_mul_f32_e32 v56, v56, v218
	v_mul_f32_e32 v58, v58, v219
	v_cvt_pk_bf16_f32 v60, v60, v62
	v_cvt_pk_bf16_f32 v61, v56, v58
	global_store_dwordx2 v[204:205], v[60:61], off
	v_mul_f32_e32 v220, v52, v176
	v_mul_f32_e32 v221, v54, v176
	v_mul_f32_e32 v222, v48, v176
	v_mul_f32_e32 v223, v50, v176
	v_mul_f32_e32 v52, v52, v53
	v_mul_f32_e32 v54, v54, v55
	v_mul_f32_e32 v48, v48, v49
	v_mul_f32_e32 v50, v50, v51
	v_exp_f32_e32 v220, v220
	v_exp_f32_e32 v221, v221
	v_exp_f32_e32 v222, v222
	v_exp_f32_e32 v223, v223
	v_fma_f32 v220, v220, v234, v234
; __device__ __forceinline__ unsigned cvt_pk_bf16(float lo, float hi) { return pk_bf16(lo, hi); }
; __device__ __forceinline__ float silu_f(float x) { return x * __builtin_amdgcn_rcpf(1.f + __builtin_amdgcn_exp2f(-x * L2E)); }
;     __device__ __forceinline__ void operator()(const f32x4 (&acc)[2][2][4][2], const Unit& u, int wr, int wc, int fr, int fq) const {
;         EPI_ROWS_BEGIN
;             const int hc = (u.pn * BM + colt) >> 1; const float r = 1.f / sqrtf(rstd[row] * (1.f / DM) + RMS_EPS);
;             const float h0 = silu_f(v0[0] * r) * (v0[1] * r), h1 = silu_f(v0[2] * r) * (v0[3] * r), h2 = silu_f(v1[0] * r) * (v1[1] * r), h3 = silu_f(v1[2] * r) * (v1[3] * r);
;             u32x2 w; w.x = cvt_pk_bf16(h0, h1); w.y = cvt_pk_bf16(h2, h3);
;             *(u32x2*)(hid + (size_t)row * HIDLD + hc) = w;
;         EPI_ROWS_END
	v_fma_f32 v221, v221, v234, v234
	v_fma_f32 v222, v222, v234, v234
	v_fma_f32 v223, v223, v234, v234
	v_rcp_f32_e32 v220, v220
	v_rcp_f32_e32 v221, v221
	v_rcp_f32_e32 v222, v222
	v_rcp_f32_e32 v223, v223
	v_mul_f32_e32 v52, v52, v220
	v_mul_f32_e32 v54, v54, v221
	v_mul_f32_e32 v48, v48, v222
	v_mul_f32_e32 v50, v50, v223
	v_cvt_pk_bf16_f32 v52, v52, v54
	v_cvt_pk_bf16_f32 v53, v48, v50
	global_store_dwordx2 v[204:205], v[52:53], off offset:128
	v_mul_f32_e32 v216, v44, v177
	v_mul_f32_e32 v217, v46, v177
	v_mul_f32_e32 v218, v40, v177
	v_mul_f32_e32 v219, v42, v177
	v_mul_f32_e32 v44, v44, v45
	v_mul_f32_e32 v46, v46, v47
	v_mul_f32_e32 v40, v40, v41
	v_mul_f32_e32 v42, v42, v43
	v_exp_f32_e32 v216, v216
	v_exp_f32_e32 v217, v217
	v_exp_f32_e32 v218, v218
	v_exp_f32_e32 v219, v219
	v_fma_f32 v216, v216, v235, v235
	v_fma_f32 v217, v217, v235, v235
	v_fma_f32 v218, v218, v235, v235
	v_fma_f32 v219, v219, v235, v235
	v_rcp_f32_e32 v216, v216
	v_rcp_f32_e32 v217, v217
	v_rcp_f32_e32 v218, v218
	v_rcp_f32_e32 v219, v219
	v_mul_f32_e32 v44, v44, v216
	v_mul_f32_e32 v46, v46, v217
	v_mul_f32_e32 v40, v40, v218
	v_mul_f32_e32 v42, v42, v219
	v_cvt_pk_bf16_f32 v44, v44, v46
	v_cvt_pk_bf16_f32 v45, v40, v42
	global_store_dwordx2 v[206:207], v[44:45], off
	v_mul_f32_e32 v220, v36, v177
	v_mul_f32_e32 v221, v38, v177
	v_mul_f32_e32 v222, v32, v177
	v_mul_f32_e32 v223, v34, v177
	v_mul_f32_e32 v36, v36, v37
	v_mul_f32_e32 v38, v38, v39
	v_mul_f32_e32 v32, v32, v33
	v_mul_f32_e32 v34, v34, v35
	v_exp_f32_e32 v220, v220
	v_exp_f32_e32 v221, v221
	v_exp_f32_e32 v222, v222
	v_exp_f32_e32 v223, v223
	v_fma_f32 v220, v220, v235, v235
	v_fma_f32 v221, v221, v235, v235
	v_fma_f32 v222, v222, v235, v235
	v_fma_f32 v223, v223, v235, v235
	v_rcp_f32_e32 v220, v220
	v_rcp_f32_e32 v221, v221
	v_rcp_f32_e32 v222, v222
	v_rcp_f32_e32 v223, v223
	v_mul_f32_e32 v36, v36, v220
	v_mul_f32_e32 v38, v38, v221
	v_mul_f32_e32 v32, v32, v222
	v_mul_f32_e32 v34, v34, v223
	v_cvt_pk_bf16_f32 v36, v36, v38
	v_cvt_pk_bf16_f32 v37, v32, v34
	global_store_dwordx2 v[206:207], v[36:37], off offset:128
	v_mul_f32_e32 v216, v28, v178
	v_mul_f32_e32 v217, v30, v178
	v_mul_f32_e32 v218, v24, v178
	v_mul_f32_e32 v219, v26, v178
	v_mul_f32_e32 v28, v28, v29
	v_mul_f32_e32 v30, v30, v31
	v_mul_f32_e32 v24, v24, v25
	v_mul_f32_e32 v26, v26, v27
	v_exp_f32_e32 v216, v216
	v_exp_f32_e32 v217, v217
	v_exp_f32_e32 v218, v218
	v_exp_f32_e32 v219, v219
	v_fma_f32 v216, v216, v236, v236
	v_fma_f32 v217, v217, v236, v236
	v_fma_f32 v218, v218, v236, v236
	v_fma_f32 v219, v219, v236, v236
	v_rcp_f32_e32 v216, v216
	v_rcp_f32_e32 v217, v217
	v_rcp_f32_e32 v218, v218
	v_rcp_f32_e32 v219, v219
	v_mul_f32_e32 v28, v28, v216
	v_mul_f32_e32 v30, v30, v217
	v_mul_f32_e32 v24, v24, v218
	v_mul_f32_e32 v26, v26, v219
	v_cvt_pk_bf16_f32 v28, v28, v30
	v_cvt_pk_bf16_f32 v29, v24, v26
	global_store_dwordx2 v[208:209], v[28:29], off
	v_mul_f32_e32 v220, v20, v178
	v_mul_f32_e32 v221, v22, v178
	v_mul_f32_e32 v222, v16, v178
	v_mul_f32_e32 v223, v18, v178
	v_mul_f32_e32 v20, v20, v21
	v_mul_f32_e32 v22, v22, v23
	v_mul_f32_e32 v16, v16, v17
	v_mul_f32_e32 v18, v18, v19
	v_exp_f32_e32 v220, v220
	v_exp_f32_e32 v221, v221
	v_exp_f32_e32 v222, v222
	v_exp_f32_e32 v223, v223
	v_fma_f32 v220, v220, v236, v236
	v_fma_f32 v221, v221, v236, v236
	v_fma_f32 v222, v222, v236, v236
	v_fma_f32 v223, v223, v236, v236
	v_rcp_f32_e32 v220, v220
	v_rcp_f32_e32 v221, v221
	v_rcp_f32_e32 v222, v222
	v_rcp_f32_e32 v223, v223
	v_mul_f32_e32 v20, v20, v220
	v_mul_f32_e32 v22, v22, v221
	v_mul_f32_e32 v16, v16, v222
	v_mul_f32_e32 v18, v18, v223
	v_cvt_pk_bf16_f32 v20, v20, v22
	v_cvt_pk_bf16_f32 v21, v16, v18
	global_store_dwordx2 v[208:209], v[20:21], off offset:128
	v_mul_f32_e32 v216, v12, v179
	v_mul_f32_e32 v217, v14, v179
	v_mul_f32_e32 v218, v8, v179
	v_mul_f32_e32 v219, v10, v179
	v_mul_f32_e32 v12, v12, v13
	v_mul_f32_e32 v14, v14, v15
	v_mul_f32_e32 v8, v8, v9
	v_mul_f32_e32 v10, v10, v11
	v_exp_f32_e32 v216, v216
	v_exp_f32_e32 v217, v217
	v_exp_f32_e32 v218, v218
	v_exp_f32_e32 v219, v219
	v_fma_f32 v216, v216, v237, v237
	v_fma_f32 v217, v217, v237, v237
	v_fma_f32 v218, v218, v237, v237
	v_fma_f32 v219, v219, v237, v237
	v_rcp_f32_e32 v216, v216
	v_rcp_f32_e32 v217, v217
	v_rcp_f32_e32 v218, v218
	v_rcp_f32_e32 v219, v219
	v_mul_f32_e32 v12, v12, v216
	v_mul_f32_e32 v14, v14, v217
	v_mul_f32_e32 v8, v8, v218
	v_mul_f32_e32 v10, v10, v219
	v_cvt_pk_bf16_f32 v12, v12, v14
	v_cvt_pk_bf16_f32 v13, v8, v10
	global_store_dwordx2 v[210:211], v[12:13], off
	v_mul_f32_e32 v220, v4, v179
	v_mul_f32_e32 v221, v6, v179
	v_mul_f32_e32 v222, v0, v179
	v_mul_f32_e32 v223, v2, v179
	v_mul_f32_e32 v4, v4, v5
	v_mul_f32_e32 v6, v6, v7
	v_mul_f32_e32 v0, v0, v1
	v_mul_f32_e32 v2, v2, v3
	v_exp_f32_e32 v220, v220
	v_exp_f32_e32 v221, v221
	v_exp_f32_e32 v222, v222
	v_exp_f32_e32 v223, v223
	v_fma_f32 v220, v220, v237, v237
	v_fma_f32 v221, v221, v237, v237
	v_fma_f32 v222, v222, v237, v237
	v_fma_f32 v223, v223, v237, v237
	v_rcp_f32_e32 v220, v220
	v_rcp_f32_e32 v221, v221
	v_rcp_f32_e32 v222, v222
	v_rcp_f32_e32 v223, v223
	v_mul_f32_e32 v4, v4, v220
	v_mul_f32_e32 v6, v6, v221
	v_mul_f32_e32 v0, v0, v222
	v_mul_f32_e32 v2, v2, v223
	v_cvt_pk_bf16_f32 v4, v4, v6
	v_cvt_pk_bf16_f32 v5, v0, v2
	global_store_dwordx2 v[210:211], v[4:5], off offset:128
	s_mov_b64 s[0:1], -1
	s_andn2_b64 vcc, exec, s[4:5]
	s_cbranch_vccnz .LBB0_1045
	s_andn2_b64 vcc, exec, s[8:9]
	s_cbranch_vccnz .LBB0_1044
	s_barrier
	s_branch .LBB0_1044

; #define PG8_STAGE(bufoff, gbase, voff) do { _Pragma("unroll") for (int _i = 0; _i < 2; ++_i) \
;         __builtin_amdgcn_global_load_lds((const unsigned*)((const char*)(gbase) + (voff)[_i]), (PG8_LAS unsigned*)(lds + (bufoff) + ldsw + _i * 8192), 16, 0, 0); } while (0)
; #define PG8_WAIT_V(n) asm volatile("s_waitcnt vmcnt(" #n ")" ::: "memory")
; #define PG8_BAR __builtin_amdgcn_s_barrier()
; template <class Epi, class Sched, bool ALIGN_EPI = false, bool SP2 = false>
; __device__ __forceinline__ void gemm_phase(PG8_LAS unsigned char* lds, const Gemm g, const Sched& S, const Epi& E) {
;     ...
;     const char* cA = PG8_UA(cur); const char* cB = PG8_UB(cur);
;     S.a_ready(cur);
;     if constexpr (SP2) {
;         PG8_STAGE(PG8_SB(0, 0), cB, voffB); PG8_STAGE(PG8_SB(0, 1), cB + hstepB, voffB); PG8_STAGE(PG8_SA(0, 0), cA, voffA); PG8_STAGE(PG8_SA(0, 1), cA + hstepA, voffA);
;         if (wr == 1) PG8_BAR;
;         PG8_WAIT_V(2); PG8_BAR;
;         PG8_STAGE(PG8_SB(1, 0), cB + kstep, voffB); PG8_STAGE(PG8_SA(1, 0), cA + kstep, voffA); PG8_STAGE(PG8_SB(1, 1), cB + hstepB + kstep, voffB);
;         PG8_WAIT_V(6); PG8_BAR;
;     } else {
;         PG8_STAGE(PG8_SB(0, 0), cB, voffB); PG8_STAGE(PG8_SA(0, 0), cA, voffA); PG8_STAGE(PG8_SB(0, 1), cB + hstepB, voffB); PG8_STAGE(PG8_SA(0, 1), cA + hstepA, voffA);
;         if (wr == 1) PG8_BAR;
;         PG8_WAIT_V(4); PG8_BAR;
;         PG8_STAGE(PG8_SB(1, 0), cB + kstep, voffB); PG8_STAGE(PG8_SA(1, 0), cA + kstep, voffA); PG8_STAGE(PG8_SB(1, 1), cB + hstepB + kstep, voffB);
;         PG8_WAIT_V(6); PG8_BAR;
;     }
;     __device__ __forceinline__ void operator()(const f32x4 (&acc)[2][2][4][2], const Unit& u, int wr, int wc, int fr, int fq) const {
;     ...
;             const int hc = (u.pn * BM + colt) >> 1; const float r = 1.f / sqrtf(rstd[row] * (1.f / DM) + RMS_EPS);
.LBB0_1525:
	s_add_u32 s10, s34, 0x7800000
	s_addc_u32 s11, s35, 0
	s_add_u32 s12, s34, 0x34a0000
	s_addc_u32 s13, s35, 0
	s_lshl_b32 s4, s4, 5
	s_mov_b64 s[14:15], 0x80
	s_and_b32 s18, s4, 0x60
	s_add_i32 m0, s42, 0x18000
	v_lshl_add_u64 v[6:7], v[6:7], 0, s[14:15]
	s_lshl_b32 s1, s3, 13
	s_lshl_b32 s16, s18, 7
	s_waitcnt vmcnt(2)
	s_barrier
	global_load_lds_dwordx4 v[6:7], off
	v_lshl_add_u64 v[4:5], v[4:5], 0, s[14:15]
	s_add_i32 m0, s42, 0x1a000
	s_add_i32 s47, s42, 0x8000
	s_add_i32 s48, s42, 0xa000
	global_load_lds_dwordx4 v[4:5], off
	v_lshl_add_u64 v[0:1], v[0:1], 0, s[14:15]
	s_mov_b32 m0, s47
	s_add_u32 s4, s26, 0x40080
	global_load_lds_dwordx4 v[0:1], off
	v_lshl_add_u64 v[0:1], v[2:3], 0, s[14:15]
	s_mov_b32 m0, s48
	s_addc_u32 s5, s27, 0
	global_load_lds_dwordx4 v[0:1], off
	s_add_i32 m0, s42, 0x1c000
	v_lshl_add_u64 v[0:1], s[4:5], 0, v[132:133]
	global_load_lds_dwordx4 v[0:1], off
	v_lshl_add_u64 v[0:1], s[4:5], 0, v[128:129]
	s_add_i32 m0, s42, 0x1e000
	v_lshlrev_b32_e32 v2, 2, v194
	global_load_lds_dwordx4 v[0:1], off
	v_and_b32_e32 v0, 15, v194
	v_lshlrev_b32_e32 v1, 1, v11
	v_lshl_or_b32 v146, s3, 6, v0
	v_lshl_or_b32 v0, v0, 6, v1
	v_and_b32_e32 v2, 32, v2
	v_bitop3_b32 v0, v0, s1, v2 bitop3:0xde
	v_lshlrev_b32_e32 v3, 6, v194
	s_movk_i32 s1, 0x3c0
	v_and_or_b32 v1, v3, s1, v1
	v_bitop3_b32 v147, s16, v1, v2 bitop3:0xf6
	v_lshlrev_b32_e32 v1, 8, v194
	v_and_b32_e32 v1, 0x38000, v1
	v_lshlrev_b32_e32 v2, 11, v12
	v_or3_b32 v1, v9, v1, v2
	v_add_u32_e32 v136, v1, v10
	v_lshlrev_b32_e32 v1, 4, v8
	s_waitcnt vmcnt(6)
	s_cmpk_lt_u32 s2, 0x100
	v_and_b32_e32 v1, 0x78000, v1
	s_cselect_b64 s[16:17], -1, 0
	v_readlane_b32 s2, v251, 13
	v_or3_b32 v1, v9, v1, v2
	s_add_i32 s51, 0, 0x10000
	s_add_i32 s52, 0, 0x14000
	s_ashr_i32 s49, s2, 31
	s_mov_b32 s50, s2
	v_or_b32_e32 v148, s18, v11
	v_mov_b32_e32 v137, v133
	v_add_u32_e32 v138, v1, v10
	v_mov_b32_e32 v139, v133
	v_mov_b64_e32 v[140:141], 0xb00
	v_mov_b64_e32 v[142:143], 0xaff
	s_waitcnt vmcnt(0)
	v_add_u32_e32 v149, s51, v147
	v_add_u32_e32 v150, s52, v147
	v_add_u32_e32 v151, 0, v0
	v_mov_b32_e32 v152, 0x358637bd
	s_mov_b32 s53, 0xf800000
	v_mov_b32_e32 v153, 0x260
	s_movk_i32 s54, 0x1680
	v_lshl_add_u32 v246, s0, 8, v146
	v_mov_b32_e32 v247, 0
	v_lshl_add_u64 v[246:247], v[246:247], 2, s[12:13]
	global_load_dword v238, v[246:247], off
	global_load_dword v239, v[246:247], off offset:64
	global_load_dword v240, v[246:247], off offset:128
	global_load_dword v241, v[246:247], off offset:192
	global_load_dword v242, v[246:247], off offset:512
	global_load_dword v243, v[246:247], off offset:576
	global_load_dword v244, v[246:247], off offset:640
	global_load_dword v245, v[246:247], off offset:704
	s_barrier
	v_readlane_b32 s3, v251, 14
	s_branch .LBB0_1528
